# speedup vs baseline: 1.0046x; 1.0046x over previous
; template <int G>
; __device__ __forceinline__ void p1_big(const Params& P, const Ptrs<G>& w, int layer, int mt, int nt, bfu* sm, int mtn, int ntn) {
;     ...
;       bfu* dp = dst + (size_t)(m0 + wr * 128 + c15) * ld + cofs + wc * 64 + 16 * g;
; #pragma unroll
;       for (int i = 0; i < 8; ++i) {
;         uint4 o0, o1;
;         o0.x = pack2(acc[i][0][0], acc[i][0][1]); o0.y = pack2(acc[i][0][2], acc[i][0][3]);
;         o0.z = pack2(acc[i][1][0], acc[i][1][1]); o0.w = pack2(acc[i][1][2], acc[i][1][3]);
;         o1.x = pack2(acc[i][2][0], acc[i][2][1]); o1.y = pack2(acc[i][2][2], acc[i][2][3]);
;         o1.z = pack2(acc[i][3][0], acc[i][3][1]); o1.w = pack2(acc[i][3][2], acc[i][3][3]);
;         *(uint4*)(dp + (size_t)(16 * i) * ld) = o0;
;         *(uint4*)(dp + (size_t)(16 * i) * ld + 8) = o1;
;       }
.LBB0_129:
	v_and_b32_e32 v128, 0xffffff80, v198
	v_add_u32_e32 v128, s16, v128
	v_or_b32_e32 v128, v128, v171
	v_mad_i64_i32 v[128:129], s[36:37], s28, v128, 0
	v_lshl_add_u64 v[128:129], v[128:129], 1, s[26:27]
	s_ashr_i32 s1, s0, 31
	v_lshl_add_u64 v[128:129], s[0:1], 1, v[128:129]
	v_lshlrev_b32_e32 v152, 7, v161
	v_lshl_add_u64 v[128:129], v[128:129], 0, v[152:153]
	v_lshlrev_b32_e32 v152, 5, v163
	v_lshl_add_u64 v[128:129], v[128:129], 0, v[152:153]
	s_lshl_b32 s2, s28, 5
	v_cvt_pk_bf16_f32 v123, v122, v123
	v_cvt_pk_bf16_f32 v122, v120, v121
	v_cvt_pk_bf16_f32 v121, v126, v127
	v_cvt_pk_bf16_f32 v120, v124, v125
	v_cvt_pk_bf16_f32 v115, v114, v115
	v_cvt_pk_bf16_f32 v114, v112, v113
	v_cvt_pk_bf16_f32 v113, v118, v119
	v_cvt_pk_bf16_f32 v112, v116, v117
	global_store_dwordx4 v[128:129], v[120:123], off
	global_store_dwordx4 v[128:129], v[112:115], off offset:16
	v_cvt_pk_bf16_f32 v107, v106, v107
	v_cvt_pk_bf16_f32 v106, v104, v105
	v_cvt_pk_bf16_f32 v105, v110, v111
	v_cvt_pk_bf16_f32 v104, v108, v109
	v_cvt_pk_bf16_f32 v99, v98, v99
	v_cvt_pk_bf16_f32 v98, v96, v97
	v_cvt_pk_bf16_f32 v97, v102, v103
	v_cvt_pk_bf16_f32 v96, v100, v101
	v_lshl_add_u64 v[112:113], v[128:129], 0, s[2:3]
	global_store_dwordx4 v[112:113], v[104:107], off
	global_store_dwordx4 v[112:113], v[96:99], off offset:16
	v_cvt_pk_bf16_f32 v91, v90, v91
	v_cvt_pk_bf16_f32 v90, v88, v89
	v_cvt_pk_bf16_f32 v89, v94, v95
	v_cvt_pk_bf16_f32 v88, v92, v93
	v_cvt_pk_bf16_f32 v83, v82, v83
	v_cvt_pk_bf16_f32 v82, v80, v81
	v_cvt_pk_bf16_f32 v81, v86, v87
	v_cvt_pk_bf16_f32 v80, v84, v85
	v_lshl_add_u64 v[96:97], v[112:113], 0, s[2:3]
	global_store_dwordx4 v[96:97], v[88:91], off
	global_store_dwordx4 v[96:97], v[80:83], off offset:16
	v_cvt_pk_bf16_f32 v75, v74, v75
	v_cvt_pk_bf16_f32 v74, v72, v73
	v_cvt_pk_bf16_f32 v73, v78, v79
	v_cvt_pk_bf16_f32 v72, v76, v77
	v_cvt_pk_bf16_f32 v67, v66, v67
	v_cvt_pk_bf16_f32 v66, v64, v65
	v_cvt_pk_bf16_f32 v65, v70, v71
	v_cvt_pk_bf16_f32 v64, v68, v69
	v_lshl_add_u64 v[80:81], v[96:97], 0, s[2:3]
	global_store_dwordx4 v[80:81], v[72:75], off
	global_store_dwordx4 v[80:81], v[64:67], off offset:16
	v_cvt_pk_bf16_f32 v59, v58, v59
	v_cvt_pk_bf16_f32 v58, v56, v57
	v_cvt_pk_bf16_f32 v57, v62, v63
	v_cvt_pk_bf16_f32 v56, v60, v61
	v_cvt_pk_bf16_f32 v51, v50, v51
	v_cvt_pk_bf16_f32 v50, v48, v49
	v_cvt_pk_bf16_f32 v49, v54, v55
	v_cvt_pk_bf16_f32 v48, v52, v53
	v_lshl_add_u64 v[64:65], v[80:81], 0, s[2:3]
	global_store_dwordx4 v[64:65], v[56:59], off
	global_store_dwordx4 v[64:65], v[48:51], off offset:16
	v_cvt_pk_bf16_f32 v43, v42, v43
	v_cvt_pk_bf16_f32 v42, v40, v41
	v_cvt_pk_bf16_f32 v41, v46, v47
	v_cvt_pk_bf16_f32 v40, v44, v45
	v_cvt_pk_bf16_f32 v35, v34, v35
	v_cvt_pk_bf16_f32 v34, v32, v33
	v_cvt_pk_bf16_f32 v33, v38, v39
	v_cvt_pk_bf16_f32 v32, v36, v37
	v_lshl_add_u64 v[48:49], v[64:65], 0, s[2:3]
	global_store_dwordx4 v[48:49], v[40:43], off
	global_store_dwordx4 v[48:49], v[32:35], off offset:16
	v_cvt_pk_bf16_f32 v27, v26, v27
	v_cvt_pk_bf16_f32 v26, v24, v25
	v_cvt_pk_bf16_f32 v25, v30, v31
	v_cvt_pk_bf16_f32 v24, v28, v29
	v_cvt_pk_bf16_f32 v19, v18, v19
	v_cvt_pk_bf16_f32 v18, v16, v17
	v_cvt_pk_bf16_f32 v17, v22, v23
	v_cvt_pk_bf16_f32 v16, v20, v21
	v_lshl_add_u64 v[32:33], v[48:49], 0, s[2:3]
	global_store_dwordx4 v[32:33], v[24:27], off
	global_store_dwordx4 v[32:33], v[16:19], off offset:16
	v_cvt_pk_bf16_f32 v11, v10, v11
	v_cvt_pk_bf16_f32 v10, v8, v9
	v_cvt_pk_bf16_f32 v9, v14, v15
	v_cvt_pk_bf16_f32 v8, v12, v13
	v_cvt_pk_bf16_f32 v3, v2, v3
	v_cvt_pk_bf16_f32 v2, v0, v1
	v_cvt_pk_bf16_f32 v1, v6, v7
	v_cvt_pk_bf16_f32 v0, v4, v5
	v_lshl_add_u64 v[16:17], v[32:33], 0, s[2:3]
	global_store_dwordx4 v[16:17], v[8:11], off
	global_store_dwordx4 v[16:17], v[0:3], off offset:16
